# direct HBM->LDS: FFN-up epilogue conv taps/bias fetched by LDS-DMA from the trailing wave-half during the last K iteration (was load-to-VGPR + ds_write at epilogue start)
# speedup vs baseline: 1.0153x; 1.0153x over previous
; #define PG8_STAGE(bufoff, gbase, voff) do { _Pragma("unroll") for (int _i = 0; _i < 2; ++_i) { \
;         const unsigned _m0 = ldsu + (unsigned)(bufoff) + ldsw + (unsigned)(_i * 8192); \
;         asm volatile("s_mov_b32 m0, %2\n\ts_nop 0\n\tglobal_load_lds_dwordx4 %0, %1" :: "v"((voff)[_i]), "s"((const char*)(gbase)), "s"(_m0) : "memory"); } } while (0)
; #define PG8_LDA(dst, b, h) do { _Pragma("unroll") for (int m = 0; m < 4; ++m) _Pragma("unroll") for (int k = 0; k < 2; ++k) dst[m][k] = *(const LAS bf16x8*)(lds + PG8_SA(b, h) + aoff + m * 2048 + k * 1024); } while (0)
; #define PG8_LDB(dst, b, h) do { _Pragma("unroll") for (int n = 0; n < 2; ++n) _Pragma("unroll") for (int k = 0; k < 2; ++k) dst[n][k] = *(const LAS bf16x8*)(lds + bbase[b][h] + n * 2048 + k * 1024); } while (0)
; #define PG8_WAIT_V(n) asm volatile("s_waitcnt vmcnt(" #n ")" ::: "memory")
; #define PG8_WAIT_L(n) asm volatile("s_waitcnt lgkmcnt(" #n ")" ::: "memory")
; #define PG8_BAR __builtin_amdgcn_s_barrier()
; #define PG8_SCHED __builtin_amdgcn_sched_barrier(0)
; template <class Epi>
; __device__ __forceinline__ void gemm_phase(LAS unsigned char* lds, const Gemm g, const StaticOrder& S, const Epi& E) {
;     ...
;         for (int t = 0; t < nt; t += 2) {
;             const bool last = (t == nt - 2);
;             const char* a2 = last ? nA : cA + (size_t)(t + 2) * kstep; const char* b2 = last ? nB : cB + (size_t)(t + 2) * kstep;
;             const char* a3 = a2 + kstep; const char* b3 = b2 + kstep;
;             const char* b1 = cB + (size_t)(t + 1) * kstep;
;             PG8_LDB(B0, 0, 0); PG8_SCHED; PG8_LDA(At, 0, 0); PG8_LDA(At2, 0, 1); PG8_STAGE(PG8_SB(1, 1), b1 + hstepB, voffB);
;             PG8_WAIT_V(8); PG8_WAIT_L(0); PG8_BAR; PG8_MMA2B(0, At, At2, B0); PG8_BAR; PG8_SCHED;
;             PG8_LDB(B0, 0, 1); PG8_STAGE(PG8_SB(0, 0), b2, voffB); PG8_STAGE(PG8_SA(0, 0), a2, voffA); PG8_STAGE(PG8_SA(0, 1), a2 + hstepA, voffA);
;             PG8_WAIT_V(8); PG8_WAIT_L(0); PG8_BAR; PG8_MMA2B(1, At, At2, B0); PG8_BAR; PG8_SCHED;
.LBB0_1027:
	ds_read_b128 v[68:71], v220
	ds_read_b128 v[84:87], v220 offset:1024
	ds_read_b128 v[88:91], v220 offset:2048
	ds_read_b128 v[92:95], v220 offset:3072
	s_add_u32 s12, s10, 0x100
	s_addc_u32 s13, s11, 0
	s_cmp_eq_u32 s69, 12
	s_cselect_b32 s14, s97, vcc_hi
	s_cselect_b32 s15, s7, s68
	s_cselect_b32 s84, vcc_lo, s12
	s_cselect_b32 s85, s39, s13
	s_add_u32 s16, s14, 0x80
	s_addc_u32 s17, s15, 0
	ds_read_b128 v[96:99], v221
	ds_read_b128 v[100:103], v221 offset:1024
	ds_read_b128 v[152:155], v221 offset:2048
	ds_read_b128 v[156:159], v221 offset:3072
	ds_read_b128 v[166:169], v221 offset:4096
	ds_read_b128 v[178:181], v221 offset:5120
	ds_read_b128 v[182:185], v221 offset:6144
	ds_read_b128 v[186:189], v221 offset:7168
	ds_read_b128 v[190:193], v221 offset:16384
	ds_read_b128 v[194:197], v221 offset:17408
	ds_read_b128 v[198:201], v221 offset:18432
	ds_read_b128 v[202:205], v221 offset:19456
	ds_read_b128 v[226:229], v221 offset:20480
	ds_read_b128 v[230:233], v221 offset:21504
	ds_read_b128 v[234:237], v221 offset:22528
	ds_read_b128 v[238:241], v221 offset:23552
	s_add_u32 s10, s10, 0x40080
	s_addc_u32 s11, s11, 0
	s_mov_b32 m0, s58
	s_nop 0
	global_load_lds_dwordx4 v217, s[10:11]
	s_mov_b32 m0, s60
	s_nop 0
	global_load_lds_dwordx4 v219, s[10:11]
	s_waitcnt vmcnt(8)
	s_waitcnt lgkmcnt(0)
	s_barrier
	v_mfma_f32_16x16x32_bf16 v[80:83], v[68:71], v[96:99], v[80:83]
	v_mfma_f32_16x16x32_bf16 v[76:79], v[88:91], v[96:99], v[76:79]
	v_mfma_f32_16x16x32_bf16 v[148:151], v[68:71], v[152:155], v[148:151]
	v_mfma_f32_16x16x32_bf16 v[52:55], v[88:91], v[152:155], v[52:55]
	v_mfma_f32_16x16x32_bf16 v[144:147], v[68:71], v[166:169], v[144:147]
	v_mfma_f32_16x16x32_bf16 v[48:51], v[88:91], v[166:169], v[48:51]
	v_mfma_f32_16x16x32_bf16 v[136:139], v[68:71], v[182:185], v[136:139]
	v_mfma_f32_16x16x32_bf16 v[40:43], v[88:91], v[182:185], v[40:43]
	v_mfma_f32_16x16x32_bf16 v[124:127], v[68:71], v[190:193], v[124:127]
	v_mfma_f32_16x16x32_bf16 v[28:31], v[88:91], v[190:193], v[28:31]
	v_mfma_f32_16x16x32_bf16 v[120:123], v[68:71], v[198:201], v[120:123]
	v_mfma_f32_16x16x32_bf16 v[24:27], v[88:91], v[198:201], v[24:27]
	v_mfma_f32_16x16x32_bf16 v[112:115], v[68:71], v[226:229], v[112:115]
	v_mfma_f32_16x16x32_bf16 v[16:19], v[88:91], v[226:229], v[16:19]
	v_mfma_f32_16x16x32_bf16 v[64:67], v[68:71], v[234:237], v[64:67]
	v_mfma_f32_16x16x32_bf16 v[4:7], v[88:91], v[234:237], v[4:7]
	v_mfma_f32_16x16x32_bf16 v[80:83], v[84:87], v[100:103], v[80:83]
	v_mfma_f32_16x16x32_bf16 v[76:79], v[92:95], v[100:103], v[76:79]
	v_mfma_f32_16x16x32_bf16 v[148:151], v[84:87], v[156:159], v[148:151]
	v_mfma_f32_16x16x32_bf16 v[52:55], v[92:95], v[156:159], v[52:55]
	v_mfma_f32_16x16x32_bf16 v[144:147], v[84:87], v[178:181], v[144:147]
	v_mfma_f32_16x16x32_bf16 v[48:51], v[92:95], v[178:181], v[48:51]
	v_mfma_f32_16x16x32_bf16 v[136:139], v[84:87], v[186:189], v[136:139]
	v_mfma_f32_16x16x32_bf16 v[40:43], v[92:95], v[186:189], v[40:43]
	v_mfma_f32_16x16x32_bf16 v[124:127], v[84:87], v[194:197], v[124:127]
	v_mfma_f32_16x16x32_bf16 v[28:31], v[92:95], v[194:197], v[28:31]
	v_mfma_f32_16x16x32_bf16 v[120:123], v[84:87], v[202:205], v[120:123]
	v_mfma_f32_16x16x32_bf16 v[24:27], v[92:95], v[202:205], v[24:27]
	v_mfma_f32_16x16x32_bf16 v[112:115], v[84:87], v[230:233], v[112:115]
	v_mfma_f32_16x16x32_bf16 v[16:19], v[92:95], v[230:233], v[16:19]
	v_mfma_f32_16x16x32_bf16 v[64:67], v[84:87], v[238:241], v[64:67]
	v_mfma_f32_16x16x32_bf16 v[4:7], v[92:95], v[238:241], v[4:7]
	s_barrier
	ds_read_b128 v[68:71], v222
	ds_read_b128 v[84:87], v222 offset:1024
	ds_read_b128 v[88:91], v222 offset:2048
	ds_read_b128 v[92:95], v222 offset:3072
	s_mov_b32 m0, s48
	s_nop 0
	global_load_lds_dwordx4 v217, s[84:85]
	s_mov_b32 m0, s49
	s_nop 0
	global_load_lds_dwordx4 v219, s[84:85]
	s_mov_b32 m0, s47
	s_nop 0
	global_load_lds_dwordx4 v216, s[14:15]
	s_mov_b32 m0, s50
	s_nop 0
	global_load_lds_dwordx4 v218, s[14:15]
	s_add_u32 s10, s14, 0x40000
	s_addc_u32 s11, s15, 0
	s_mov_b32 m0, s51
	s_nop 0
	global_load_lds_dwordx4 v216, s[10:11]
	s_mov_b32 m0, s52
	s_nop 0
	global_load_lds_dwordx4 v218, s[10:11]
	s_waitcnt vmcnt(8)
	s_waitcnt lgkmcnt(0)
	s_barrier
	v_mfma_f32_16x16x32_bf16 v[72:75], v[68:71], v[96:99], v[72:75]
	v_mfma_f32_16x16x32_bf16 v[56:59], v[88:91], v[96:99], v[56:59]
	v_mfma_f32_16x16x32_bf16 v[44:47], v[88:91], v[152:155], v[44:47]
	v_mfma_f32_16x16x32_bf16 v[36:39], v[88:91], v[166:169], v[36:39]
	v_mfma_f32_16x16x32_bf16 v[128:131], v[68:71], v[182:185], v[128:131]
	v_mfma_f32_16x16x32_bf16 v[32:35], v[88:91], v[182:185], v[32:35]
	v_mfma_f32_16x16x32_bf16 v[116:119], v[68:71], v[190:193], v[116:119]
	v_mfma_f32_16x16x32_bf16 v[20:23], v[88:91], v[190:193], v[20:23]
	v_mfma_f32_16x16x32_bf16 v[108:111], v[68:71], v[198:201], v[108:111]
	v_mfma_f32_16x16x32_bf16 v[12:15], v[88:91], v[198:201], v[12:15]
	v_mfma_f32_16x16x32_bf16 v[104:107], v[68:71], v[226:229], v[104:107]
	v_mfma_f32_16x16x32_bf16 v[8:11], v[88:91], v[226:229], v[8:11]
	v_mfma_f32_16x16x32_bf16 v[60:63], v[68:71], v[234:237], v[60:63]
	v_mfma_f32_16x16x32_bf16 v[0:3], v[88:91], v[234:237], v[0:3]
	v_mfma_f32_16x16x32_bf16 v[72:75], v[84:87], v[100:103], v[72:75]
	v_mfma_f32_16x16x32_bf16 v[56:59], v[92:95], v[100:103], v[56:59]
	v_mfma_f32_16x16x32_bf16 v[96:99], v[68:71], v[152:155], v[140:143]
	v_mfma_f32_16x16x32_bf16 v[44:47], v[92:95], v[156:159], v[44:47]
	v_mfma_f32_16x16x32_bf16 v[100:103], v[68:71], v[166:169], v[132:135]
	v_mfma_f32_16x16x32_bf16 v[36:39], v[92:95], v[178:181], v[36:39]
	v_mfma_f32_16x16x32_bf16 v[128:131], v[84:87], v[186:189], v[128:131]
	v_mfma_f32_16x16x32_bf16 v[32:35], v[92:95], v[186:189], v[32:35]
	v_mfma_f32_16x16x32_bf16 v[116:119], v[84:87], v[194:197], v[116:119]
	v_mfma_f32_16x16x32_bf16 v[20:23], v[92:95], v[194:197], v[20:23]
	v_mfma_f32_16x16x32_bf16 v[108:111], v[84:87], v[202:205], v[108:111]
	v_mfma_f32_16x16x32_bf16 v[12:15], v[92:95], v[202:205], v[12:15]
	v_mfma_f32_16x16x32_bf16 v[104:107], v[84:87], v[230:233], v[104:107]
	v_mfma_f32_16x16x32_bf16 v[8:11], v[92:95], v[230:233], v[8:11]
	v_mfma_f32_16x16x32_bf16 v[60:63], v[84:87], v[238:241], v[60:63]
	v_mfma_f32_16x16x32_bf16 v[0:3], v[92:95], v[238:241], v[0:3]
	v_mfma_f32_16x16x32_bf16 v[96:99], v[84:87], v[156:159], v[96:99]
	v_mfma_f32_16x16x32_bf16 v[100:103], v[84:87], v[178:181], v[100:103]
	s_barrier
; #define LAS __attribute__((address_space(3)))
; #define PG8_STAGE(bufoff, gbase, voff) do { _Pragma("unroll") for (int _i = 0; _i < 2; ++_i) { \
;         const unsigned _m0 = ldsu + (unsigned)(bufoff) + ldsw + (unsigned)(_i * 8192); \
;         asm volatile("s_mov_b32 m0, %2\n\ts_nop 0\n\tglobal_load_lds_dwordx4 %0, %1" :: "v"((voff)[_i]), "s"((const char*)(gbase)), "s"(_m0) : "memory"); } } while (0)
; #define PG8_LDA(dst, b, h) do { _Pragma("unroll") for (int m = 0; m < 4; ++m) _Pragma("unroll") for (int k = 0; k < 2; ++k) dst[m][k] = *(const LAS bf16x8*)(lds + PG8_SA(b, h) + aoff + m * 2048 + k * 1024); } while (0)
; #define PG8_LDB(dst, b, h) do { _Pragma("unroll") for (int n = 0; n < 2; ++n) _Pragma("unroll") for (int k = 0; k < 2; ++k) dst[n][k] = *(const LAS bf16x8*)(lds + bbase[b][h] + n * 2048 + k * 1024); } while (0)
; #define PG8_WAIT_V(n) asm volatile("s_waitcnt vmcnt(" #n ")" ::: "memory")
; #define PG8_WAIT_L(n) asm volatile("s_waitcnt lgkmcnt(" #n ")" ::: "memory")
; #define PG8_BAR __builtin_amdgcn_s_barrier()
; #define PG8_SCHED __builtin_amdgcn_sched_barrier(0)
; template <class Epi>
; __device__ __forceinline__ void gemm_phase(LAS unsigned char* lds, const Gemm g, const StaticOrder& S, const Epi& E) {
;     ...
;             PG8_LDB(B0, 1, 0); PG8_SCHED; PG8_LDA(At, 1, 0); PG8_LDA(At2, 1, 1); PG8_STAGE(PG8_SB(0, 1), b2 + hstepB, voffB);
;             PG8_WAIT_V(8); PG8_WAIT_L(0); PG8_BAR; PG8_MMA2B(0, At, At2, B0); PG8_BAR; PG8_SCHED;
;             PG8_LDB(B0, 1, 1); PG8_STAGE(PG8_SB(1, 0), b3, voffB); PG8_STAGE(PG8_SA(1, 0), a3, voffA); PG8_STAGE(PG8_SA(1, 1), a3 + hstepA, voffA);
;     __device__ __forceinline__ void operator()(f32x4 (&acc)[2][2][4][2], const Unit& u, int wr, int wc, int fr, int fq) const {
;     ...
;           else { const int which = t >> 6, j = (t & 63) * 4, bj = j >> 7, c = j & 127; const float* src = (which < 3 ? cw + (size_t)which * NUP : cb) + bj * DFF + u.pn * 128 + c;
;               *(LAS f32x4*)(cwL + which * 256 + j) = *(const f32x4*)src; } }
	ds_read_b128 v[68:71], v223
	ds_read_b128 v[84:87], v223 offset:1024
	ds_read_b128 v[88:91], v223 offset:2048
	ds_read_b128 v[92:95], v223 offset:3072
	ds_read_b128 v[132:135], v221 offset:32768
	ds_read_b128 v[140:143], v221 offset:33792
	ds_read_b128 v[152:155], v221 offset:34816
	ds_read_b128 v[156:159], v221 offset:35840
	ds_read_b128 v[166:169], v221 offset:36864
	ds_read_b128 v[178:181], v221 offset:37888
	ds_read_b128 v[182:185], v221 offset:38912
	ds_read_b128 v[186:189], v221 offset:39936
	ds_read_b128 v[190:193], v221 offset:49152
	ds_read_b128 v[194:197], v221 offset:50176
	ds_read_b128 v[198:201], v221 offset:51200
	ds_read_b128 v[202:205], v221 offset:52224
	ds_read_b128 v[226:229], v221 offset:53248
	ds_read_b128 v[230:233], v221 offset:54272
	ds_read_b128 v[234:237], v221 offset:55296
	ds_read_b128 v[238:241], v221 offset:56320
	s_add_u32 s10, s84, 0x40000
	s_addc_u32 s11, s85, 0
	s_mov_b32 m0, s53
	s_nop 0
	global_load_lds_dwordx4 v217, s[10:11]
	s_mov_b32 m0, s54
	s_nop 0
	global_load_lds_dwordx4 v219, s[10:11]
	s_waitcnt vmcnt(8)
	s_waitcnt lgkmcnt(0)
	s_barrier
	v_mfma_f32_16x16x32_bf16 v[80:83], v[68:71], v[132:135], v[80:83]
	v_mfma_f32_16x16x32_bf16 v[76:79], v[88:91], v[132:135], v[76:79]
	v_mfma_f32_16x16x32_bf16 v[148:151], v[68:71], v[152:155], v[148:151]
	v_mfma_f32_16x16x32_bf16 v[52:55], v[88:91], v[152:155], v[52:55]
	v_mfma_f32_16x16x32_bf16 v[144:147], v[68:71], v[166:169], v[144:147]
	v_mfma_f32_16x16x32_bf16 v[48:51], v[88:91], v[166:169], v[48:51]
	v_mfma_f32_16x16x32_bf16 v[136:139], v[68:71], v[182:185], v[136:139]
	v_mfma_f32_16x16x32_bf16 v[40:43], v[88:91], v[182:185], v[40:43]
	v_mfma_f32_16x16x32_bf16 v[124:127], v[68:71], v[190:193], v[124:127]
	v_mfma_f32_16x16x32_bf16 v[28:31], v[88:91], v[190:193], v[28:31]
	v_mfma_f32_16x16x32_bf16 v[120:123], v[68:71], v[198:201], v[120:123]
	v_mfma_f32_16x16x32_bf16 v[24:27], v[88:91], v[198:201], v[24:27]
	v_mfma_f32_16x16x32_bf16 v[112:115], v[68:71], v[226:229], v[112:115]
	v_mfma_f32_16x16x32_bf16 v[16:19], v[88:91], v[226:229], v[16:19]
	v_mfma_f32_16x16x32_bf16 v[64:67], v[68:71], v[234:237], v[64:67]
	v_mfma_f32_16x16x32_bf16 v[4:7], v[88:91], v[234:237], v[4:7]
	v_mfma_f32_16x16x32_bf16 v[80:83], v[84:87], v[140:143], v[80:83]
	v_mfma_f32_16x16x32_bf16 v[76:79], v[92:95], v[140:143], v[76:79]
	v_mfma_f32_16x16x32_bf16 v[148:151], v[84:87], v[156:159], v[148:151]
	v_mfma_f32_16x16x32_bf16 v[52:55], v[92:95], v[156:159], v[52:55]
	v_mfma_f32_16x16x32_bf16 v[144:147], v[84:87], v[178:181], v[144:147]
	v_mfma_f32_16x16x32_bf16 v[48:51], v[92:95], v[178:181], v[48:51]
	v_mfma_f32_16x16x32_bf16 v[136:139], v[84:87], v[186:189], v[136:139]
	v_mfma_f32_16x16x32_bf16 v[40:43], v[92:95], v[186:189], v[40:43]
	v_mfma_f32_16x16x32_bf16 v[124:127], v[84:87], v[194:197], v[124:127]
	v_mfma_f32_16x16x32_bf16 v[28:31], v[92:95], v[194:197], v[28:31]
	v_mfma_f32_16x16x32_bf16 v[120:123], v[84:87], v[202:205], v[120:123]
	v_mfma_f32_16x16x32_bf16 v[24:27], v[92:95], v[202:205], v[24:27]
	v_mfma_f32_16x16x32_bf16 v[112:115], v[84:87], v[230:233], v[112:115]
	v_mfma_f32_16x16x32_bf16 v[16:19], v[92:95], v[230:233], v[16:19]
	v_mfma_f32_16x16x32_bf16 v[64:67], v[84:87], v[238:241], v[64:67]
	v_mfma_f32_16x16x32_bf16 v[4:7], v[92:95], v[238:241], v[4:7]
	s_barrier
	s_add_u32 s10, s84, 0x80
	ds_read_b128 v[68:71], v224
	ds_read_b128 v[84:87], v224 offset:1024
	ds_read_b128 v[88:91], v224 offset:2048
	ds_read_b128 v[92:95], v224 offset:3072
	s_addc_u32 s11, s85, 0
	s_mov_b32 m0, s88
	s_nop 0
	global_load_lds_dwordx4 v217, s[10:11]
	s_mov_b32 m0, s89
	s_nop 0
	global_load_lds_dwordx4 v219, s[10:11]
	s_mov_b32 m0, s95
	s_nop 0
	global_load_lds_dwordx4 v216, s[16:17]
	s_mov_b32 m0, s37
	s_nop 0
	global_load_lds_dwordx4 v218, s[16:17]
	s_add_u32 s10, s14, 0x40080
	s_addc_u32 s11, s15, 0
	s_mov_b32 m0, s56
	s_nop 0
	global_load_lds_dwordx4 v216, s[10:11]
	s_mov_b32 m0, s57
	s_nop 0
	global_load_lds_dwordx4 v218, s[10:11]
	s_cmp_eq_u32 s69, 12
	s_cbranch_scc0 .Lcw_skip
	s_cmp_eq_u64 s[4:5], 0
	s_cbranch_scc1 .Lcw_skip
	v_lshlrev_b32_e32 v242, 4, v215
	v_add3_u32 v242, v214, s59, v242
	s_lshr_b32 s32, s59, 6
	s_mul_i32 s98, s32, 0x5800
	s_add_u32 s98, s0, s98
	s_addc_u32 s99, s1, 0
	s_cmp_lt_u32 s32, 3
	s_cselect_b32 s98, s98, s2
	s_cselect_b32 s99, s99, s3
	s_lshl_b32 s32, s67, 9
	s_add_u32 s98, s98, s32
	s_addc_u32 s99, s99, 0
	v_bfe_u32 v243, v242, 5, 1
	v_mul_u32_u24_e32 v243, 0x2c00, v243
	v_and_b32_e32 v244, 31, v242
	v_lshl_add_u32 v243, v244, 4, v243
	v_readlane_b32 s32, v252, 44
	s_nop 3
	s_lshl_b32 m0, s59, 4
	s_add_u32 m0, m0, s32
	s_nop 0
	global_load_lds_dwordx4 v243, s[98:99]
; #define LAS __attribute__((address_space(3)))
; #define PG8_WAIT_V(n) asm volatile("s_waitcnt vmcnt(" #n ")" ::: "memory")
; #define PG8_WAIT_L(n) asm volatile("s_waitcnt lgkmcnt(" #n ")" ::: "memory")
; #define PG8_BAR __builtin_amdgcn_s_barrier()
; #define PG8_SCHED __builtin_amdgcn_sched_barrier(0)
; template <class Epi>
; __device__ __forceinline__ void gemm_phase(LAS unsigned char* lds, const Gemm g, const StaticOrder& S, const Epi& E) {
;     ...
;             PG8_WAIT_V(8); PG8_WAIT_L(0); PG8_BAR; PG8_MMA2B(1, At, At2, B0); PG8_BAR; PG8_SCHED;
;         }
;         if (wr == 0) PG8_BAR;
;     __device__ __forceinline__ void operator()(f32x4 (&acc)[2][2][4][2], const Unit& u, int wr, int wc, int fr, int fq) const {
;     ...
;         const int row0 = u.pm * 256 + wr * 64 + fr, colg0 = u.pn * 128 + wc * 32 + 8 * fq;
;         LAS float* rsL = hl + 2048; LAS float* cwL = hl + 2304;
;         { const int t = (wc * 4 + fq) * 16 + fr;
;           if (wr == 0) { const float* sp = ssq + ((size_t)u.pm * 256 + t) * 16; const f32x4 a = *(const f32x4*)sp, b = *(const f32x4*)(sp + 4), c = *(const f32x4*)(sp + 8), d = *(const f32x4*)(sp + 12);
;               const f32x4 q = (a + b) + (c + d); rsL[t] = rsqrtf(((q[0] + q[1]) + (q[2] + q[3])) * (1.0f / 1024.0f) + EPS); }
;           else { const int which = t >> 6, j = (t & 63) * 4, bj = j >> 7, c = j & 127; const float* src = (which < 3 ? cw + (size_t)which * NUP : cb) + bj * DFF + u.pn * 128 + c;
;               *(LAS f32x4*)(cwL + which * 256 + j) = *(const f32x4*)src; } }
.Lcw_skip:
	s_waitcnt vmcnt(8)
	s_waitcnt lgkmcnt(0)
	s_barrier
	v_mfma_f32_16x16x32_bf16 v[72:75], v[68:71], v[132:135], v[72:75]
	v_mfma_f32_16x16x32_bf16 v[56:59], v[88:91], v[132:135], v[56:59]
	v_mfma_f32_16x16x32_bf16 v[96:99], v[68:71], v[152:155], v[96:99]
	v_mfma_f32_16x16x32_bf16 v[72:75], v[84:87], v[140:143], v[72:75]
	v_mfma_f32_16x16x32_bf16 v[56:59], v[92:95], v[140:143], v[56:59]
	v_mfma_f32_16x16x32_bf16 v[140:143], v[84:87], v[156:159], v[96:99]
	v_mfma_f32_16x16x32_bf16 v[96:99], v[68:71], v[166:169], v[100:103]
	v_mfma_f32_16x16x32_bf16 v[132:135], v[84:87], v[178:181], v[96:99]
	v_mfma_f32_16x16x32_bf16 v[96:99], v[68:71], v[182:185], v[128:131]
	v_mfma_f32_16x16x32_bf16 v[128:131], v[84:87], v[186:189], v[96:99]
	v_mfma_f32_16x16x32_bf16 v[96:99], v[68:71], v[190:193], v[116:119]
	v_mfma_f32_16x16x32_bf16 v[116:119], v[84:87], v[194:197], v[96:99]
	v_mfma_f32_16x16x32_bf16 v[96:99], v[68:71], v[198:201], v[108:111]
	v_mfma_f32_16x16x32_bf16 v[44:47], v[88:91], v[152:155], v[44:47]
	v_mfma_f32_16x16x32_bf16 v[36:39], v[88:91], v[166:169], v[36:39]
	v_mfma_f32_16x16x32_bf16 v[32:35], v[88:91], v[182:185], v[32:35]
	v_mfma_f32_16x16x32_bf16 v[20:23], v[88:91], v[190:193], v[20:23]
	v_mfma_f32_16x16x32_bf16 v[108:111], v[84:87], v[202:205], v[96:99]
	v_mfma_f32_16x16x32_bf16 v[12:15], v[88:91], v[198:201], v[12:15]
	v_mfma_f32_16x16x32_bf16 v[96:99], v[68:71], v[226:229], v[104:107]
	v_mfma_f32_16x16x32_bf16 v[8:11], v[88:91], v[226:229], v[8:11]
	v_mfma_f32_16x16x32_bf16 v[60:63], v[68:71], v[234:237], v[60:63]
	v_mfma_f32_16x16x32_bf16 v[0:3], v[88:91], v[234:237], v[0:3]
	v_mfma_f32_16x16x32_bf16 v[44:47], v[92:95], v[156:159], v[44:47]
	v_mfma_f32_16x16x32_bf16 v[36:39], v[92:95], v[178:181], v[36:39]
	v_mfma_f32_16x16x32_bf16 v[32:35], v[92:95], v[186:189], v[32:35]
	v_mfma_f32_16x16x32_bf16 v[20:23], v[92:95], v[194:197], v[20:23]
	v_mfma_f32_16x16x32_bf16 v[12:15], v[92:95], v[202:205], v[12:15]
	v_mfma_f32_16x16x32_bf16 v[104:107], v[84:87], v[230:233], v[96:99]
	v_mfma_f32_16x16x32_bf16 v[8:11], v[92:95], v[230:233], v[8:11]
	v_mfma_f32_16x16x32_bf16 v[60:63], v[84:87], v[238:241], v[60:63]
	v_mfma_f32_16x16x32_bf16 v[0:3], v[92:95], v[238:241], v[0:3]
	s_barrier
	s_add_i32 s69, s69, 2
	s_add_u32 vcc_hi, vcc_hi, 0x100
	s_addc_u32 s68, s68, 0
	s_cmp_gt_u32 s69, 13
	s_mov_b64 s[10:11], s[12:13]
	s_cbranch_scc0 .LBB0_1027
	s_and_b64 vcc, exec, s[90:91]
	s_cbranch_vccz .LBB0_1030
	v_lshlrev_b32_e32 v68, 4, v215
	v_add3_u32 v68, v214, s59, v68
	s_ashr_i32 s97, s96, 31
	s_lshl_b64 s[12:13], s[96:97], 14
	v_ashrrev_i32_e32 v69, 31, v68
	s_add_u32 s12, s18, s12
	s_addc_u32 s13, s19, s13
	v_lshlrev_b64 v[70:71], 6, v[68:69]
	v_lshl_add_u64 v[70:71], s[12:13], 0, v[70:71]
	global_load_dwordx4 v[86:89], v[70:71], off
	global_load_dwordx4 v[90:93], v[70:71], off offset:16
	global_load_dwordx4 v[94:97], v[70:71], off offset:32
	global_load_dwordx4 v[98:101], v[70:71], off offset:48
	s_barrier
.LBB0_1030:
	v_mov_b32_e32 v188, v214
	v_mov_b32_e32 v84, v215
	s_lshl_b32 s10, s67, 7
	v_lshlrev_b32_e32 v68, 4, v84
	v_add3_u32 v68, v188, s59, v68
	s_mov_b64 s[12:13], -1
	s_and_b64 vcc, exec, s[4:5]
	s_cbranch_vccz .LBB0_1034
	v_ashrrev_i32_e32 v69, 6, v68
	v_cmp_gt_i32_e32 vcc, 3, v69
	v_mov_b64_e32 v[70:71], s[2:3]
	s_and_saveexec_b64 s[12:13], vcc
	v_mov_b64_e32 v[70:71], s[0:1]
	s_movk_i32 s7, 0x5800
	v_mad_i64_i32 v[70:71], s[14:15], v69, s7, v[70:71]
	s_or_b64 exec, exec, s[12:13]
	v_lshlrev_b32_e32 v85, 2, v68
	v_bfe_u32 v86, v85, 7, 1
	v_mul_u32_u24_e32 v86, 0xb00, v86
	v_lshlrev_b32_e32 v160, 2, v86
	v_lshl_add_u64 v[70:71], v[70:71], 0, v[160:161]
	s_ashr_i32 s11, s10, 31
	v_lshlrev_b32_e32 v86, 4, v68
	v_lshl_add_u64 v[70:71], s[10:11], 2, v[70:71]
	v_and_b32_e32 v160, 0x1f0, v86
	v_lshl_add_u64 v[70:71], v[70:71], 0, v[160:161]
	v_and_b32_e32 v70, 0xfc, v85
	v_lshlrev_b32_e32 v69, 10, v69
	v_lshlrev_b32_e32 v70, 2, v70
	v_readlane_b32 s7, v252, 44
	s_mov_b64 s[12:13], 0
	s_nop 0
	v_add3_u32 v69, s7, v69, v70
